# attention ping-pong with one s_barrier per tile per wave half (mid barriers removed: only the period boundary orders LDS ring writes vs reads)
# baseline (speedup 1.0000x reference)
; #define LAS __attribute__((address_space(3)))
; __device__ __forceinline__ void attn_unit(KParams& P, int l, const AUnit& U, LAS unsigned char* lds) {
;     ...
;     for (int t = 0; t < U.nt; ++t) {
;         const bool more = t + 1 < U.nt;
;         if (more) A_LOAD(t + 1);
;         const LAS unsigned char* bb = lds + (t & 1) * ABUF;
;         f32x16 p0, p1;
; #pragma unroll
;         for (int r = 0; r < 16; ++r) { p0[r] = 0.f; p1[r] = 0.f; }
; #pragma unroll
;         for (int s = 0; s < 10; ++s) {
;             const bf16x8 k0 = *(const LAS bf16x8*)(bb + koff + 32 * s), k1 = *(const LAS bf16x8*)(bb + koff + 32 * KT_PITCH + 32 * s);
;             p0 = __builtin_amdgcn_mfma_f32_32x32x16_bf16(k0, qf[s], p0, 0, 0, 0);
;             p1 = __builtin_amdgcn_mfma_f32_32x32x16_bf16(k1, qf[s], p1, 0, 0, 0);
;         }
.Lattn_noload_entry:
	s_waitcnt lgkmcnt(0)
.Lattn_x0:
	s_mov_b32 s23, 0
	s_mov_b32 s24, 0x9c00
	v_add3_u32 v230, s23, v187, v156
	ds_read_b128 v[192:195], v230
	ds_read_b128 v[196:199], v230 offset:10752
	ds_read_b128 v[200:203], v230 offset:32
	ds_read_b128 v[204:207], v230 offset:10784
	ds_read_b128 v[208:211], v230 offset:64
	ds_read_b128 v[226:229], v230 offset:10816
	s_waitcnt lgkmcnt(5)
	v_mfma_f32_32x32x16_bf16 v[80:95], v[192:195], v[96:99], v[232:247]
	ds_read_b128 v[248:251], v230 offset:96
	s_waitcnt lgkmcnt(5)
	v_mfma_f32_32x32x16_bf16 v[64:79], v[196:199], v[96:99], v[232:247]
	ds_read_b128 v[192:195], v230 offset:10848
	s_waitcnt lgkmcnt(5)
	v_mfma_f32_32x32x16_bf16 v[80:95], v[200:203], v[100:103], v[80:95]
	ds_read_b128 v[196:199], v230 offset:128
	s_waitcnt lgkmcnt(5)
	v_mfma_f32_32x32x16_bf16 v[64:79], v[204:207], v[100:103], v[64:79]
	ds_read_b128 v[200:203], v230 offset:10880
	s_waitcnt lgkmcnt(5)
	v_mfma_f32_32x32x16_bf16 v[80:95], v[208:211], v[104:107], v[80:95]
	ds_read_b128 v[204:207], v230 offset:160
	s_waitcnt lgkmcnt(5)
	v_mfma_f32_32x32x16_bf16 v[64:79], v[226:229], v[104:107], v[64:79]
	ds_read_b128 v[208:211], v230 offset:10912
	s_waitcnt lgkmcnt(5)
	v_mfma_f32_32x32x16_bf16 v[80:95], v[248:251], v[108:111], v[80:95]
	ds_read_b128 v[226:229], v230 offset:192
	s_waitcnt lgkmcnt(5)
	v_mfma_f32_32x32x16_bf16 v[64:79], v[192:195], v[108:111], v[64:79]
	ds_read_b128 v[248:251], v230 offset:10944
	s_waitcnt lgkmcnt(5)
	v_mfma_f32_32x32x16_bf16 v[80:95], v[196:199], v[112:115], v[80:95]
	ds_read_b128 v[192:195], v230 offset:224
	s_waitcnt lgkmcnt(5)
	v_mfma_f32_32x32x16_bf16 v[64:79], v[200:203], v[112:115], v[64:79]
	ds_read_b128 v[196:199], v230 offset:10976
	s_waitcnt lgkmcnt(5)
	v_mfma_f32_32x32x16_bf16 v[80:95], v[204:207], v[116:119], v[80:95]
	ds_read_b128 v[200:203], v230 offset:256
	s_waitcnt lgkmcnt(5)
	v_mfma_f32_32x32x16_bf16 v[64:79], v[208:211], v[116:119], v[64:79]
	ds_read_b128 v[204:207], v230 offset:11008
	s_waitcnt lgkmcnt(5)
	v_mfma_f32_32x32x16_bf16 v[80:95], v[226:229], v[120:123], v[80:95]
	ds_read_b128 v[208:211], v230 offset:288
	s_waitcnt lgkmcnt(5)
	v_mfma_f32_32x32x16_bf16 v[64:79], v[248:251], v[120:123], v[64:79]
	ds_read_b128 v[226:229], v230 offset:11040
	s_waitcnt lgkmcnt(5)
	v_mfma_f32_32x32x16_bf16 v[80:95], v[192:195], v[124:127], v[80:95]
	s_waitcnt lgkmcnt(4)
	v_mfma_f32_32x32x16_bf16 v[64:79], v[196:199], v[124:127], v[64:79]
	s_waitcnt lgkmcnt(3)
	v_mfma_f32_32x32x16_bf16 v[80:95], v[200:203], v[128:131], v[80:95]
	s_waitcnt lgkmcnt(2)
	v_mfma_f32_32x32x16_bf16 v[64:79], v[204:207], v[128:131], v[64:79]
	s_waitcnt lgkmcnt(1)
	v_mfma_f32_32x32x16_bf16 v[80:95], v[208:211], v[132:135], v[80:95]
	s_waitcnt lgkmcnt(0)
	v_mfma_f32_32x32x16_bf16 v[64:79], v[226:229], v[132:135], v[64:79]
	s_waitcnt lgkmcnt(0)
	s_mov_b32 s22, 0
	s_mov_b32 s23, 0x9c00
	s_mov_b32 s24, 0x13800
.Lattn_loop:
	s_cmp_lt_u32 s88, 4
	s_cbranch_scc1 .Lattn_nobar1
	s_barrier
.Lattn_nobar1:
	s_setprio 2
	s_cmp_lt_u32 s88, 4
	s_cselect_b32 s29, s23, s24
	s_cselect_b32 s30, 2, 3
	s_add_i32 s30, s30, s20
	s_waitcnt vmcnt(0)
	v_add_u32_e32 v221, s29, v216
	ds_write_b128 v221, v[136:139]
	v_add_u32_e32 v221, s29, v217
	ds_write_b128 v221, v[140:143]
	v_add_u32_e32 v221, s29, v218
	ds_write_b128 v221, v[144:147]
	v_add_u32_e32 v221, s29, v219
	ds_write_b128 v221, v[148:151] offset:21504
	v_add_u32_e32 v221, s29, v220
	ds_write_b128 v221, v[152:155] offset:21504
	s_cmp_lt_u32 s30, s89
	s_cbranch_scc0 .Lattn_noload_y
	global_load_dwordx4 v[136:139], v174, s[40:41]
	global_load_dwordx4 v[140:143], v176, s[40:41]
	global_load_dwordx4 v[144:147], v178, s[40:41]
	global_load_dwordx4 v[148:151], v[170:171], off
	global_load_dwordx4 v[152:155], v[172:173], off
	s_add_u32 s40, s40, 0x5000
	s_addc_u32 s41, s41, 0
	v_lshl_add_u64 v[170:171], v[170:171], 0, s[82:83]
	v_lshl_add_u64 v[172:173], v[172:173], 0, s[82:83]

; #define LAS __attribute__((address_space(3)))
; __device__ __forceinline__ unsigned cvt_pk_bf16(float lo, float hi) { f32x2 v = {lo, hi}; bf16x2_t b = __builtin_convertvector(v, bf16x2_t); return __builtin_bit_cast(unsigned, b); }
; __device__ __forceinline__ void attn_unit(KParams& P, int l, const AUnit& U, LAS unsigned char* lds) {
;     ...
;         const float mnew = fmaxf(mrun, mx); const float f = __builtin_amdgcn_exp2f(mrun - mnew); const bool grew = __any(mnew > mrun); mrun = mnew;
;         f32x2 ps2 = {0.f, 0.f}; const f32x2 nm2 = {-mnew, -mnew};
; #pragma unroll
;         for (int r = 0; r < 16; r += 2) { f32x2 a = (f32x2){p0[r], p0[r + 1]} + nm2, b = (f32x2){p1[r], p1[r + 1]} + nm2;
;             a[0] = __builtin_amdgcn_exp2f(a[0]); a[1] = __builtin_amdgcn_exp2f(a[1]); b[0] = __builtin_amdgcn_exp2f(b[0]); b[1] = __builtin_amdgcn_exp2f(b[1]);
;             p0[r] = a[0]; p0[r + 1] = a[1]; p1[r] = b[0]; p1[r + 1] = b[1]; ps2 += a; ps2 += b; }
;         const float ps = ps2[0] + ps2[1];
;         lrun = lrun * f + ps;
;     ...
;         bf16x8 pf[4];
;         { u32x4 w;
;           w.x = cvt_pk_bf16(p0[0], p0[1]); w.y = cvt_pk_bf16(p0[2], p0[3]); w.z = cvt_pk_bf16(p0[4], p0[5]); w.w = cvt_pk_bf16(p0[6], p0[7]); pf[0] = __builtin_bit_cast(bf16x8, w);
;           w.x = cvt_pk_bf16(p0[8], p0[9]); w.y = cvt_pk_bf16(p0[10], p0[11]); w.z = cvt_pk_bf16(p0[12], p0[13]); w.w = cvt_pk_bf16(p0[14], p0[15]); pf[1] = __builtin_bit_cast(bf16x8, w);
;           w.x = cvt_pk_bf16(p1[0], p1[1]); w.y = cvt_pk_bf16(p1[2], p1[3]); w.z = cvt_pk_bf16(p1[4], p1[5]); w.w = cvt_pk_bf16(p1[6], p1[7]); pf[2] = __builtin_bit_cast(bf16x8, w);
;           w.x = cvt_pk_bf16(p1[8], p1[9]); w.y = cvt_pk_bf16(p1[10], p1[11]); w.z = cvt_pk_bf16(p1[12], p1[13]); w.w = cvt_pk_bf16(p1[14], p1[15]); pf[3] = __builtin_bit_cast(bf16x8, w); }
; #pragma unroll
;         for (int d = 0; d < 4; ++d)
; #pragma unroll
;             for (int ks = 0; ks < 4; ++ks) {
;                 const bf16x8 vf = *(const LAS bf16x8*)(bb + voff + d * 32 * VT_PITCH + 32 * ks);
.Lattn_fast:
	v_exp_f32_e32 v80, v80
	v_exp_f32_e32 v81, v81
	v_exp_f32_e32 v82, v82
	v_exp_f32_e32 v83, v83
	v_exp_f32_e32 v84, v84
	v_exp_f32_e32 v85, v85
	v_exp_f32_e32 v86, v86
	v_exp_f32_e32 v87, v87
	v_exp_f32_e32 v88, v88
	v_exp_f32_e32 v89, v89
	v_exp_f32_e32 v90, v90
	v_exp_f32_e32 v91, v91
	v_exp_f32_e32 v92, v92
	v_exp_f32_e32 v93, v93
	v_exp_f32_e32 v94, v94
	v_exp_f32_e32 v95, v95
	v_add_f32_e32 v208, v80, v81
	v_add_f32_e32 v208, v208, v82
	v_add_f32_e32 v208, v208, v83
	v_add_f32_e32 v208, v208, v84
	v_add_f32_e32 v208, v208, v85
	v_add_f32_e32 v208, v208, v86
	v_add_f32_e32 v208, v208, v87
	v_exp_f32_e32 v64, v64
	v_exp_f32_e32 v65, v65
	v_exp_f32_e32 v66, v66
	v_exp_f32_e32 v67, v67
	v_exp_f32_e32 v68, v68
	v_exp_f32_e32 v69, v69
	v_exp_f32_e32 v70, v70
	v_exp_f32_e32 v71, v71
	v_add_f32_e32 v209, v88, v89
	v_add_f32_e32 v209, v209, v90
	v_add_f32_e32 v209, v209, v91
	v_add_f32_e32 v209, v209, v92
	v_add_f32_e32 v209, v209, v93
	v_add_f32_e32 v209, v209, v94
	v_add_f32_e32 v209, v209, v95
	v_cvt_pk_bf16_f32 v80, v80, v81
	v_cvt_pk_bf16_f32 v81, v82, v83
	v_cvt_pk_bf16_f32 v82, v84, v85
	v_cvt_pk_bf16_f32 v83, v86, v87
	v_exp_f32_e32 v72, v72
	v_exp_f32_e32 v73, v73
	v_exp_f32_e32 v74, v74
	v_exp_f32_e32 v75, v75
	v_exp_f32_e32 v76, v76
	v_exp_f32_e32 v77, v77
	v_exp_f32_e32 v78, v78
	v_exp_f32_e32 v79, v79
	v_add_f32_e32 v210, v64, v65
	v_add_f32_e32 v210, v210, v66
	v_add_f32_e32 v210, v210, v67
	v_add_f32_e32 v210, v210, v68
	v_add_f32_e32 v210, v210, v69
	v_add_f32_e32 v210, v210, v70
	v_add_f32_e32 v210, v210, v71
	v_cvt_pk_bf16_f32 v84, v88, v89
	v_cvt_pk_bf16_f32 v85, v90, v91
	v_cvt_pk_bf16_f32 v86, v92, v93
	v_cvt_pk_bf16_f32 v87, v94, v95
	v_add_f32_e32 v211, v72, v73
	v_add_f32_e32 v211, v211, v74
	v_add_f32_e32 v211, v211, v75
	v_add_f32_e32 v211, v211, v76
	v_add_f32_e32 v211, v211, v77
	v_add_f32_e32 v211, v211, v78
	v_add_f32_e32 v211, v211, v79
	v_cvt_pk_bf16_f32 v64, v64, v65
	v_cvt_pk_bf16_f32 v65, v66, v67
	v_cvt_pk_bf16_f32 v66, v68, v69
	v_cvt_pk_bf16_f32 v67, v70, v71
	v_cvt_pk_bf16_f32 v68, v72, v73
	v_cvt_pk_bf16_f32 v69, v74, v75
	v_cvt_pk_bf16_f32 v70, v76, v77
	v_cvt_pk_bf16_f32 v71, v78, v79
	v_add_f32_e32 v208, v208, v209
	v_add_f32_e32 v210, v210, v211
	v_add_f32_e32 v208, v208, v210
	v_add_f32_e32 v167, v167, v208
	s_waitcnt lgkmcnt(0)
	v_add3_u32 v231, s22, v165, v156
	ds_read_b128 v[192:195], v231 offset:21504
	ds_read_b128 v[196:199], v231 offset:21536
	ds_read_b128 v[200:203], v231 offset:21568
	ds_read_b128 v[204:207], v231 offset:21600
	ds_read_b128 v[208:211], v231 offset:26112
	ds_read_b128 v[226:229], v231 offset:26144
	s_setprio 0
	s_cmp_lt_u32 s88, 4
	s_cbranch_scc0 .Lattn_nobar2
	s_barrier
; #define LAS __attribute__((address_space(3)))
; #define A_STORE(buf) do { LAS unsigned char* bb = lds + (buf) * ABUF; \
;         *(LAS u32x4*)(bb + kr1 * KT_PITCH + kc1 * 16) = st[0]; *(LAS u32x4*)(bb + kr2 * KT_PITCH + kc2 * 16) = st[1]; *(LAS u32x4*)(bb + kr3 * KT_PITCH + kc3 * 16) = st[2]; \
;         *(LAS u32x4*)(bb + KT_BYTES + vd1 * VT_PITCH + vc * 16) = st[3]; *(LAS u32x4*)(bb + KT_BYTES + vd2 * VT_PITCH + vc * 16) = st[4]; } while (0)
; __device__ __forceinline__ void attn_unit(KParams& P, int l, const AUnit& U, LAS unsigned char* lds) {
;     ...
;         for (int s = 0; s < 10; ++s) {
;             const bf16x8 k0 = *(const LAS bf16x8*)(bb + koff + 32 * s), k1 = *(const LAS bf16x8*)(bb + koff + 32 * KT_PITCH + 32 * s);
;             p0 = __builtin_amdgcn_mfma_f32_32x32x16_bf16(k0, qf[s], p0, 0, 0, 0);
;             p1 = __builtin_amdgcn_mfma_f32_32x32x16_bf16(k1, qf[s], p1, 0, 0, 0);
;         }
;     ...
; #pragma unroll
;         for (int d = 0; d < 4; ++d)
; #pragma unroll
;             for (int ks = 0; ks < 4; ++ks) {
;                 const bf16x8 vf = *(const LAS bf16x8*)(bb + voff + d * 32 * VT_PITCH + 32 * ks);
;                 o[d] = __builtin_amdgcn_mfma_f32_32x32x16_bf16(vf, pf[ks], o[d], 0, 0, 0);
;             }
;         if (more) A_STORE((t + 1) & 1);
;         __syncthreads();
;     }
.Lattn_nobar2:
	s_add_i32 s25, s20, 1
	s_cmp_lt_u32 s25, s89
	s_cbranch_scc0 .Lattn_xlast
	v_add3_u32 v230, s23, v187, v156
	s_waitcnt lgkmcnt(5)
	v_mfma_f32_32x32x16_bf16 v[48:63], v[192:195], v[80:83], v[48:63]
	ds_read_b128 v[248:251], v231 offset:26176
	s_waitcnt lgkmcnt(5)
	v_mfma_f32_32x32x16_bf16 v[48:63], v[196:199], v[84:87], v[48:63]
	ds_read_b128 v[192:195], v231 offset:26208
	s_waitcnt lgkmcnt(5)
	v_mfma_f32_32x32x16_bf16 v[48:63], v[200:203], v[64:67], v[48:63]
	ds_read_b128 v[196:199], v231 offset:30720
	s_waitcnt lgkmcnt(5)
	v_mfma_f32_32x32x16_bf16 v[48:63], v[204:207], v[68:71], v[48:63]
	ds_read_b128 v[200:203], v231 offset:30752
	s_waitcnt lgkmcnt(5)
	v_mfma_f32_32x32x16_bf16 v[32:47], v[208:211], v[80:83], v[32:47]
	ds_read_b128 v[204:207], v231 offset:30784
	s_waitcnt lgkmcnt(5)
	v_mfma_f32_32x32x16_bf16 v[32:47], v[226:229], v[84:87], v[32:47]
	ds_read_b128 v[208:211], v231 offset:30816
	s_waitcnt lgkmcnt(5)
	v_mfma_f32_32x32x16_bf16 v[32:47], v[248:251], v[64:67], v[32:47]
	ds_read_b128 v[226:229], v231 offset:35328
	s_waitcnt lgkmcnt(5)
	v_mfma_f32_32x32x16_bf16 v[32:47], v[192:195], v[68:71], v[32:47]
	ds_read_b128 v[248:251], v231 offset:35360
	s_waitcnt lgkmcnt(5)
	v_mfma_f32_32x32x16_bf16 v[16:31], v[196:199], v[80:83], v[16:31]
	ds_read_b128 v[192:195], v231 offset:35392
	s_waitcnt lgkmcnt(5)
	v_mfma_f32_32x32x16_bf16 v[16:31], v[200:203], v[84:87], v[16:31]
	ds_read_b128 v[196:199], v231 offset:35424
	s_waitcnt lgkmcnt(5)
	v_mfma_f32_32x32x16_bf16 v[16:31], v[204:207], v[64:67], v[16:31]
	ds_read_b128 v[200:203], v230
	s_waitcnt lgkmcnt(5)
	v_mfma_f32_32x32x16_bf16 v[16:31], v[208:211], v[68:71], v[16:31]
	ds_read_b128 v[204:207], v230 offset:10752
	s_waitcnt lgkmcnt(5)
	v_mfma_f32_32x32x16_bf16 v[0:15], v[226:229], v[80:83], v[0:15]
	ds_read_b128 v[208:211], v230 offset:32
	s_waitcnt lgkmcnt(5)
	v_mfma_f32_32x32x16_bf16 v[0:15], v[248:251], v[84:87], v[0:15]
	ds_read_b128 v[226:229], v230 offset:10784
	s_waitcnt lgkmcnt(5)
	v_mfma_f32_32x32x16_bf16 v[0:15], v[192:195], v[64:67], v[0:15]
	ds_read_b128 v[248:251], v230 offset:64
	s_waitcnt lgkmcnt(5)
	v_mfma_f32_32x32x16_bf16 v[0:15], v[196:199], v[68:71], v[0:15]
	ds_read_b128 v[192:195], v230 offset:10816
	s_waitcnt lgkmcnt(5)
	v_mfma_f32_32x32x16_bf16 v[80:95], v[200:203], v[96:99], v[232:247]
	ds_read_b128 v[196:199], v230 offset:96
	s_waitcnt lgkmcnt(5)
	v_mfma_f32_32x32x16_bf16 v[64:79], v[204:207], v[96:99], v[232:247]
	ds_read_b128 v[200:203], v230 offset:10848
	s_waitcnt lgkmcnt(5)
	v_mfma_f32_32x32x16_bf16 v[80:95], v[208:211], v[100:103], v[80:95]
	ds_read_b128 v[204:207], v230 offset:128
	s_waitcnt lgkmcnt(5)
	v_mfma_f32_32x32x16_bf16 v[64:79], v[226:229], v[100:103], v[64:79]
	ds_read_b128 v[208:211], v230 offset:10880
	s_waitcnt lgkmcnt(5)
	v_mfma_f32_32x32x16_bf16 v[80:95], v[248:251], v[104:107], v[80:95]
	ds_read_b128 v[226:229], v230 offset:160
	s_waitcnt lgkmcnt(5)
	v_mfma_f32_32x32x16_bf16 v[64:79], v[192:195], v[104:107], v[64:79]
	ds_read_b128 v[248:251], v230 offset:10912
	s_waitcnt lgkmcnt(5)
	v_mfma_f32_32x32x16_bf16 v[80:95], v[196:199], v[108:111], v[80:95]
	ds_read_b128 v[192:195], v230 offset:192
	s_waitcnt lgkmcnt(5)
	v_mfma_f32_32x32x16_bf16 v[64:79], v[200:203], v[108:111], v[64:79]
	ds_read_b128 v[196:199], v230 offset:10944
	s_waitcnt lgkmcnt(5)
	v_mfma_f32_32x32x16_bf16 v[80:95], v[204:207], v[112:115], v[80:95]
	ds_read_b128 v[200:203], v230 offset:224
	s_waitcnt lgkmcnt(5)
	v_mfma_f32_32x32x16_bf16 v[64:79], v[208:211], v[112:115], v[64:79]
	ds_read_b128 v[204:207], v230 offset:10976
	s_waitcnt lgkmcnt(5)
	v_mfma_f32_32x32x16_bf16 v[80:95], v[226:229], v[116:119], v[80:95]
	ds_read_b128 v[208:211], v230 offset:256
	s_waitcnt lgkmcnt(5)
	v_mfma_f32_32x32x16_bf16 v[64:79], v[248:251], v[116:119], v[64:79]
	ds_read_b128 v[226:229], v230 offset:11008
	s_waitcnt lgkmcnt(5)
	v_mfma_f32_32x32x16_bf16 v[80:95], v[192:195], v[120:123], v[80:95]
	ds_read_b128 v[248:251], v230 offset:288
	s_waitcnt lgkmcnt(5)
	v_mfma_f32_32x32x16_bf16 v[64:79], v[196:199], v[120:123], v[64:79]
	ds_read_b128 v[192:195], v230 offset:11040
	s_waitcnt lgkmcnt(5)
	v_mfma_f32_32x32x16_bf16 v[80:95], v[200:203], v[124:127], v[80:95]
	s_waitcnt lgkmcnt(4)
	v_mfma_f32_32x32x16_bf16 v[64:79], v[204:207], v[124:127], v[64:79]
	s_waitcnt lgkmcnt(3)
	v_mfma_f32_32x32x16_bf16 v[80:95], v[208:211], v[128:131], v[80:95]
	s_waitcnt lgkmcnt(2)
	v_mfma_f32_32x32x16_bf16 v[64:79], v[226:229], v[128:131], v[64:79]
	s_waitcnt lgkmcnt(1)
	v_mfma_f32_32x32x16_bf16 v[80:95], v[248:251], v[132:135], v[80:95]
	s_waitcnt lgkmcnt(0)
	v_mfma_f32_32x32x16_bf16 v[64:79], v[192:195], v[132:135], v[64:79]
	s_waitcnt lgkmcnt(0)
	s_mov_b32 s25, s22
	s_mov_b32 s22, s23
	s_mov_b32 s23, s24
	s_mov_b32 s24, s25
	s_add_i32 s20, s20, 1
	s_branch .Lattn_loop
.Lattn_xlast:
	s_waitcnt lgkmcnt(5)
	v_mfma_f32_32x32x16_bf16 v[48:63], v[192:195], v[80:83], v[48:63]
	ds_read_b128 v[248:251], v231 offset:26176
	s_waitcnt lgkmcnt(5)
	v_mfma_f32_32x32x16_bf16 v[48:63], v[196:199], v[84:87], v[48:63]
	ds_read_b128 v[192:195], v231 offset:26208
	s_waitcnt lgkmcnt(5)
	v_mfma_f32_32x32x16_bf16 v[48:63], v[200:203], v[64:67], v[48:63]
	ds_read_b128 v[196:199], v231 offset:30720
	s_waitcnt lgkmcnt(5)
	v_mfma_f32_32x32x16_bf16 v[48:63], v[204:207], v[68:71], v[48:63]
	ds_read_b128 v[200:203], v231 offset:30752
	s_waitcnt lgkmcnt(5)
	v_mfma_f32_32x32x16_bf16 v[32:47], v[208:211], v[80:83], v[32:47]
	ds_read_b128 v[204:207], v231 offset:30784
	s_waitcnt lgkmcnt(5)
	v_mfma_f32_32x32x16_bf16 v[32:47], v[226:229], v[84:87], v[32:47]
	ds_read_b128 v[208:211], v231 offset:30816
	s_waitcnt lgkmcnt(5)
	v_mfma_f32_32x32x16_bf16 v[32:47], v[248:251], v[64:67], v[32:47]
	ds_read_b128 v[226:229], v231 offset:35328
	s_waitcnt lgkmcnt(5)
	v_mfma_f32_32x32x16_bf16 v[32:47], v[192:195], v[68:71], v[32:47]
	ds_read_b128 v[248:251], v231 offset:35360
	s_waitcnt lgkmcnt(5)
	v_mfma_f32_32x32x16_bf16 v[16:31], v[196:199], v[80:83], v[16:31]
	ds_read_b128 v[192:195], v231 offset:35392
	s_waitcnt lgkmcnt(5)
	v_mfma_f32_32x32x16_bf16 v[16:31], v[200:203], v[84:87], v[16:31]
	ds_read_b128 v[196:199], v231 offset:35424
	s_waitcnt lgkmcnt(5)
	v_mfma_f32_32x32x16_bf16 v[16:31], v[204:207], v[64:67], v[16:31]
	s_waitcnt lgkmcnt(4)
	v_mfma_f32_32x32x16_bf16 v[16:31], v[208:211], v[68:71], v[16:31]
	s_waitcnt lgkmcnt(3)
	v_mfma_f32_32x32x16_bf16 v[0:15], v[226:229], v[80:83], v[0:15]
	s_waitcnt lgkmcnt(2)
	v_mfma_f32_32x32x16_bf16 v[0:15], v[248:251], v[84:87], v[0:15]
	s_waitcnt lgkmcnt(1)
	v_mfma_f32_32x32x16_bf16 v[0:15], v[192:195], v[64:67], v[0:15]
	s_waitcnt lgkmcnt(0)
	v_mfma_f32_32x32x16_bf16 v[0:15], v[196:199], v[68:71], v[0:15]
	s_waitcnt lgkmcnt(0)
.Lattn_done:
	s_nop 15
	s_nop 3
	v_mov_b32_e32 v64, v167
	s_branch .LBB0_688
